# GEMM main loops: LDS-DMA loads issued in scalar-base + 32-bit lane-offset form (no per-load v_lshl_add_u64), on top of deleted s_setprio flips
# speedup vs baseline: 1.0069x; 1.0069x over previous
; #define PG8_STAGE(bufoff, gbase, voff) do { _Pragma("unroll") for (int _i = 0; _i < 2; ++_i) \
;         __builtin_amdgcn_global_load_lds((const unsigned*)((const char*)(gbase) + (voff)[_i]), (LAS unsigned*)(lds + (bufoff) + ldsw + _i * 8192), 16, 0, 0); } while (0)
; #define PG8_LDA(dst, b, h) do { _Pragma("unroll") for (int m = 0; m < 4; ++m) _Pragma("unroll") for (int k = 0; k < 2; ++k) dst[m][k] = *(const LAS bf16x8*)(lds + PG8_SA(b, h) + aoff + m * 2048 + k * 1024); } while (0)
; #define PG8_LDB(dst, b, h) do { _Pragma("unroll") for (int n = 0; n < 2; ++n) _Pragma("unroll") for (int k = 0; k < 2; ++k) dst[n][k] = *(const LAS bf16x8*)(lds + PG8_SB(b, h) + boff + n * 2048 + k * 1024); } while (0)
; #define PG8_MMA(ai, bj, At, Bt) do { __builtin_amdgcn_s_setprio(1); _Pragma("unroll") for (int m = 0; m < 4; ++m) _Pragma("unroll") for (int n = 0; n < 2; ++n) _Pragma("unroll") for (int k = 0; k < 2; ++k) \
;         acc[ai][bj][m][n] = __builtin_amdgcn_mfma_f32_16x16x32_bf16(Bt[n][k], At[m][k], acc[ai][bj][m][n], 0, 0, 0); __builtin_amdgcn_s_setprio(0); } while (0)
; #define PG8_WAIT_V(n) asm volatile("s_waitcnt vmcnt(" #n ")" ::: "memory")
; #define PG8_WAIT_L(n) asm volatile("s_waitcnt lgkmcnt(" #n ")" ::: "memory")
; #define PG8_BAR __builtin_amdgcn_s_barrier()
; #define PG8_SCHED __builtin_amdgcn_sched_barrier(0)
; template <class Epi>
; __device__ __forceinline__ void gemm_phase(LAS unsigned char* lds, const Gemm g, const StaticOrder& S, const Epi& E) {
;     ...
;             PG8_LDB(B0, 0, 0); PG8_SCHED; PG8_LDA(At, 0, 0); PG8_STAGE(PG8_SA(1, 1), a1 + hstep, voffA);
;             PG8_WAIT_L(8); PG8_BAR; PG8_WAIT_L(0); PG8_MMA(0, 0, At, B0); PG8_BAR; PG8_SCHED;
;             PG8_LDB(B1, 0, 1); PG8_STAGE(PG8_SB(0, 0), b2, voffB);
;             PG8_BAR; PG8_WAIT_L(0); PG8_MMA(0, 1, At, B1); PG8_BAR;
;             PG8_LDA(At, 0, 1); PG8_STAGE(PG8_SA(0, 0), a2, voffA);
;             PG8_BAR; PG8_WAIT_L(0); PG8_MMA(1, 0, At, B0); PG8_BAR; PG8_SCHED;
;             PG8_STAGE(PG8_SB(0, 1), b2 + hstep, voffB);
;             PG8_WAIT_V(6); PG8_BAR; PG8_MMA(1, 1, At, B1); PG8_BAR;
.LBB0_119:
	s_add_i32 s41, s16, 2
	s_add_u32 s18, s14, 0x80
	s_addc_u32 s17, s15, 0
	s_add_i32 s42, 0, 0x10000
	v_add_u32_e32 v140, s42, v245
	ds_read_b128 v[128:131], v140
	ds_read_b128 v[132:135], v140 offset:1024
	ds_read_b128 v[136:139], v140 offset:2048
	ds_read_b128 v[140:143], v140 offset:3072
	s_cmp_eq_u32 s31, s16
	s_cselect_b32 s16, s10, s18
	s_cselect_b32 s17, s11, s17
	s_cselect_b32 s19, s13, s40
	s_cselect_b32 s18, s12, s39
	s_add_i32 m0, s24, 0xc000
	ds_read_b128 v[144:147], v247
	ds_read_b128 v[148:151], v247 offset:1024
	ds_read_b128 v[152:155], v247 offset:2048
	ds_read_b128 v[156:159], v247 offset:3072
	ds_read_b128 v[160:163], v247 offset:4096
	ds_read_b128 v[164:167], v247 offset:5120
	ds_read_b128 v[168:171], v247 offset:6144
	ds_read_b128 v[172:175], v247 offset:7168
	global_load_lds_dwordx4 v210, s[14:15]
	s_add_i32 m0, s24, 0xe000
	s_nop 0
	global_load_lds_dwordx4 v208, s[14:15]
	s_waitcnt lgkmcnt(8)
	s_barrier
	s_waitcnt lgkmcnt(0)
	s_waitcnt lgkmcnt(0)
	v_mfma_f32_16x16x32_bf16 v[124:127], v[128:131], v[144:147], v[124:127]
	v_mfma_f32_16x16x32_bf16 v[120:123], v[136:139], v[144:147], v[120:123]
	v_mfma_f32_16x16x32_bf16 v[108:111], v[128:131], v[152:155], v[108:111]
	v_mfma_f32_16x16x32_bf16 v[104:107], v[136:139], v[152:155], v[104:107]
	v_mfma_f32_16x16x32_bf16 v[92:95], v[128:131], v[160:163], v[92:95]
	v_mfma_f32_16x16x32_bf16 v[88:91], v[136:139], v[160:163], v[88:91]
	v_mfma_f32_16x16x32_bf16 v[76:79], v[128:131], v[168:171], v[76:79]
	v_mfma_f32_16x16x32_bf16 v[72:75], v[136:139], v[168:171], v[72:75]
	v_mfma_f32_16x16x32_bf16 v[124:127], v[132:135], v[148:151], v[124:127]
	v_mfma_f32_16x16x32_bf16 v[120:123], v[140:143], v[148:151], v[120:123]
	v_mfma_f32_16x16x32_bf16 v[108:111], v[132:135], v[156:159], v[108:111]
	v_mfma_f32_16x16x32_bf16 v[104:107], v[140:143], v[156:159], v[104:107]
	v_mfma_f32_16x16x32_bf16 v[92:95], v[132:135], v[164:167], v[92:95]
	v_mfma_f32_16x16x32_bf16 v[88:91], v[140:143], v[164:167], v[88:91]
	v_mfma_f32_16x16x32_bf16 v[76:79], v[132:135], v[172:175], v[76:79]
	v_mfma_f32_16x16x32_bf16 v[72:75], v[140:143], v[172:175], v[72:75]
	s_barrier
	s_add_i32 s43, 0, 0x14000
	s_add_i32 s42, s42, s23
	v_add_u32_e32 v188, s43, v245
	s_add_u32 s80, s18, 0x80
	s_addc_u32 s81, s19, 0
	s_mov_b32 m0, s42
	ds_read_b128 v[176:179], v188
	ds_read_b128 v[180:183], v188 offset:1024
	ds_read_b128 v[184:187], v188 offset:2048
	ds_read_b128 v[188:191], v188 offset:3072
	global_load_lds_dwordx4 v194, s[18:19]
	s_add_i32 m0, s42, 0x2000
	s_nop 0
	global_load_lds_dwordx4 v206, s[18:19]
	s_barrier
	s_waitcnt lgkmcnt(0)
	s_waitcnt lgkmcnt(0)
	v_mfma_f32_16x16x32_bf16 v[116:119], v[176:179], v[144:147], v[116:119]
	v_mfma_f32_16x16x32_bf16 v[112:115], v[184:187], v[144:147], v[112:115]
	v_mfma_f32_16x16x32_bf16 v[100:103], v[176:179], v[152:155], v[100:103]
	v_mfma_f32_16x16x32_bf16 v[96:99], v[184:187], v[152:155], v[96:99]
	v_mfma_f32_16x16x32_bf16 v[84:87], v[176:179], v[160:163], v[84:87]
	v_mfma_f32_16x16x32_bf16 v[80:83], v[184:187], v[160:163], v[80:83]
	v_mfma_f32_16x16x32_bf16 v[68:71], v[176:179], v[168:171], v[68:71]
	v_mfma_f32_16x16x32_bf16 v[64:67], v[184:187], v[168:171], v[64:67]
	v_mfma_f32_16x16x32_bf16 v[116:119], v[180:183], v[148:151], v[116:119]
	v_mfma_f32_16x16x32_bf16 v[112:115], v[188:191], v[148:151], v[112:115]
	v_mfma_f32_16x16x32_bf16 v[100:103], v[180:183], v[156:159], v[100:103]
	v_mfma_f32_16x16x32_bf16 v[96:99], v[188:191], v[156:159], v[96:99]
	v_mfma_f32_16x16x32_bf16 v[84:87], v[180:183], v[164:167], v[84:87]
	v_mfma_f32_16x16x32_bf16 v[80:83], v[188:191], v[164:167], v[80:83]
	v_mfma_f32_16x16x32_bf16 v[68:71], v[180:183], v[172:175], v[68:71]
	v_mfma_f32_16x16x32_bf16 v[64:67], v[188:191], v[172:175], v[64:67]
	s_mov_b32 m0, s24
	s_add_u32 s82, s16, 0x80
	s_addc_u32 s83, s17, 0
	s_barrier
	ds_read_b128 v[144:147], v247 offset:16384
	ds_read_b128 v[148:151], v247 offset:17408
	ds_read_b128 v[152:155], v247 offset:18432
	ds_read_b128 v[156:159], v247 offset:19456
	ds_read_b128 v[160:163], v247 offset:20480
	ds_read_b128 v[164:167], v247 offset:21504
	ds_read_b128 v[168:171], v247 offset:22528
	ds_read_b128 v[172:175], v247 offset:23552
	global_load_lds_dwordx4 v202, s[16:17]
	s_mov_b32 m0, s25
	s_nop 0
	global_load_lds_dwordx4 v204, s[16:17]
	s_barrier
	s_waitcnt lgkmcnt(0)
	s_waitcnt lgkmcnt(0)
	v_mfma_f32_16x16x32_bf16 v[60:63], v[128:131], v[144:147], v[60:63]
	v_mfma_f32_16x16x32_bf16 v[56:59], v[136:139], v[144:147], v[56:59]
	v_mfma_f32_16x16x32_bf16 v[44:47], v[128:131], v[152:155], v[44:47]
	v_mfma_f32_16x16x32_bf16 v[40:43], v[136:139], v[152:155], v[40:43]
	v_mfma_f32_16x16x32_bf16 v[28:31], v[128:131], v[160:163], v[28:31]
	v_mfma_f32_16x16x32_bf16 v[24:27], v[136:139], v[160:163], v[24:27]
	v_mfma_f32_16x16x32_bf16 v[12:15], v[128:131], v[168:171], v[12:15]
	v_mfma_f32_16x16x32_bf16 v[8:11], v[136:139], v[168:171], v[8:11]
	v_mfma_f32_16x16x32_bf16 v[60:63], v[132:135], v[148:151], v[60:63]
	v_mfma_f32_16x16x32_bf16 v[56:59], v[140:143], v[148:151], v[56:59]
	v_mfma_f32_16x16x32_bf16 v[44:47], v[132:135], v[156:159], v[44:47]
	v_mfma_f32_16x16x32_bf16 v[40:43], v[140:143], v[156:159], v[40:43]
	v_mfma_f32_16x16x32_bf16 v[28:31], v[132:135], v[164:167], v[28:31]
	v_mfma_f32_16x16x32_bf16 v[24:27], v[140:143], v[164:167], v[24:27]
	v_mfma_f32_16x16x32_bf16 v[12:15], v[132:135], v[172:175], v[12:15]
	v_mfma_f32_16x16x32_bf16 v[8:11], v[140:143], v[172:175], v[8:11]
	s_barrier
	s_add_u32 s18, s18, s0
	s_addc_u32 s19, s19, s1
	s_add_i32 s42, s43, s23
	s_add_u32 s84, s18, 0x80
	s_addc_u32 s85, s19, 0
	s_mov_b32 m0, s42
	s_nop 0
	global_load_lds_dwordx4 v194, s[18:19]
	s_add_i32 m0, s42, 0x2000
	s_nop 0
	global_load_lds_dwordx4 v206, s[18:19]
	s_waitcnt vmcnt(6)
	s_barrier
; #define PG8_STAGE(bufoff, gbase, voff) do { _Pragma("unroll") for (int _i = 0; _i < 2; ++_i) \
;         __builtin_amdgcn_global_load_lds((const unsigned*)((const char*)(gbase) + (voff)[_i]), (LAS unsigned*)(lds + (bufoff) + ldsw + _i * 8192), 16, 0, 0); } while (0)
; #define PG8_LDA(dst, b, h) do { _Pragma("unroll") for (int m = 0; m < 4; ++m) _Pragma("unroll") for (int k = 0; k < 2; ++k) dst[m][k] = *(const LAS bf16x8*)(lds + PG8_SA(b, h) + aoff + m * 2048 + k * 1024); } while (0)
; #define PG8_LDB(dst, b, h) do { _Pragma("unroll") for (int n = 0; n < 2; ++n) _Pragma("unroll") for (int k = 0; k < 2; ++k) dst[n][k] = *(const LAS bf16x8*)(lds + PG8_SB(b, h) + boff + n * 2048 + k * 1024); } while (0)
; #define PG8_MMA(ai, bj, At, Bt) do { __builtin_amdgcn_s_setprio(1); _Pragma("unroll") for (int m = 0; m < 4; ++m) _Pragma("unroll") for (int n = 0; n < 2; ++n) _Pragma("unroll") for (int k = 0; k < 2; ++k) \
;         acc[ai][bj][m][n] = __builtin_amdgcn_mfma_f32_16x16x32_bf16(Bt[n][k], At[m][k], acc[ai][bj][m][n], 0, 0, 0); __builtin_amdgcn_s_setprio(0); } while (0)
; #define PG8_WAIT_V(n) asm volatile("s_waitcnt vmcnt(" #n ")" ::: "memory")
; #define PG8_WAIT_L(n) asm volatile("s_waitcnt lgkmcnt(" #n ")" ::: "memory")
; #define PG8_BAR __builtin_amdgcn_s_barrier()
; #define PG8_SCHED __builtin_amdgcn_sched_barrier(0)
; template <class Epi>
; __device__ __forceinline__ void gemm_phase(LAS unsigned char* lds, const Gemm g, const StaticOrder& S, const Epi& E) {
;     ...
;             PG8_WAIT_V(6); PG8_BAR; PG8_MMA(1, 1, At, B1); PG8_BAR;
;             PG8_LDB(B0, 1, 0); PG8_SCHED; PG8_LDA(At, 1, 0); PG8_STAGE(PG8_SA(0, 1), a2 + hstep, voffA);
;             PG8_WAIT_L(8); PG8_BAR; PG8_WAIT_L(0); PG8_MMA(0, 0, At, B0); PG8_BAR; PG8_SCHED;
;             PG8_LDB(B1, 1, 1); PG8_STAGE(PG8_SB(1, 0), b3, voffB);
;             PG8_BAR; PG8_WAIT_L(0); PG8_MMA(0, 1, At, B1); PG8_BAR;
;             PG8_LDA(At, 1, 1); PG8_STAGE(PG8_SA(1, 0), a3, voffA);
;             PG8_BAR; PG8_WAIT_L(0); PG8_MMA(1, 0, At, B0); PG8_BAR; PG8_SCHED;
;             PG8_STAGE(PG8_SB(1, 1), b3 + hstep, voffB);
	v_mfma_f32_16x16x32_bf16 v[52:55], v[176:179], v[144:147], v[52:55]
	v_mfma_f32_16x16x32_bf16 v[48:51], v[184:187], v[144:147], v[48:51]
	v_mfma_f32_16x16x32_bf16 v[36:39], v[176:179], v[152:155], v[36:39]
	v_mfma_f32_16x16x32_bf16 v[32:35], v[184:187], v[152:155], v[32:35]
	v_mfma_f32_16x16x32_bf16 v[20:23], v[176:179], v[160:163], v[20:23]
	v_mfma_f32_16x16x32_bf16 v[16:19], v[184:187], v[160:163], v[16:19]
	v_mfma_f32_16x16x32_bf16 v[4:7], v[176:179], v[168:171], v[4:7]
	v_mfma_f32_16x16x32_bf16 v[0:3], v[184:187], v[168:171], v[0:3]
	v_mfma_f32_16x16x32_bf16 v[52:55], v[180:183], v[148:151], v[52:55]
	v_mfma_f32_16x16x32_bf16 v[48:51], v[188:191], v[148:151], v[48:51]
	v_mfma_f32_16x16x32_bf16 v[36:39], v[180:183], v[156:159], v[36:39]
	v_mfma_f32_16x16x32_bf16 v[32:35], v[188:191], v[156:159], v[32:35]
	v_mfma_f32_16x16x32_bf16 v[20:23], v[180:183], v[164:167], v[20:23]
	v_mfma_f32_16x16x32_bf16 v[16:19], v[188:191], v[164:167], v[16:19]
	v_mfma_f32_16x16x32_bf16 v[4:7], v[180:183], v[172:175], v[4:7]
	v_mfma_f32_16x16x32_bf16 v[0:3], v[188:191], v[172:175], v[0:3]
	s_add_i32 s18, 0, 0x18000
	v_add_u32_e32 v140, s18, v245
	s_barrier
	ds_read_b128 v[128:131], v140
	ds_read_b128 v[132:135], v140 offset:1024
	ds_read_b128 v[136:139], v140 offset:2048
	ds_read_b128 v[140:143], v140 offset:3072
	s_add_u32 s16, s16, s0
	s_addc_u32 s17, s17, s1
	s_mov_b32 m0, s26
	ds_read_b128 v[144:147], v247 offset:32768
	ds_read_b128 v[148:151], v247 offset:33792
	ds_read_b128 v[152:155], v247 offset:34816
	ds_read_b128 v[156:159], v247 offset:35840
	ds_read_b128 v[160:163], v247 offset:36864
	ds_read_b128 v[164:167], v247 offset:37888
	ds_read_b128 v[168:171], v247 offset:38912
	ds_read_b128 v[172:175], v247 offset:39936
	global_load_lds_dwordx4 v202, s[16:17]
	s_mov_b32 m0, s27
	s_nop 0
	global_load_lds_dwordx4 v204, s[16:17]
	s_waitcnt lgkmcnt(8)
	s_barrier
	s_waitcnt lgkmcnt(0)
	s_waitcnt lgkmcnt(0)
	v_mfma_f32_16x16x32_bf16 v[124:127], v[128:131], v[144:147], v[124:127]
	v_mfma_f32_16x16x32_bf16 v[120:123], v[136:139], v[144:147], v[120:123]
	v_mfma_f32_16x16x32_bf16 v[108:111], v[128:131], v[152:155], v[108:111]
	v_mfma_f32_16x16x32_bf16 v[104:107], v[136:139], v[152:155], v[104:107]
	v_mfma_f32_16x16x32_bf16 v[92:95], v[128:131], v[160:163], v[92:95]
	v_mfma_f32_16x16x32_bf16 v[88:91], v[136:139], v[160:163], v[88:91]
	v_mfma_f32_16x16x32_bf16 v[76:79], v[128:131], v[168:171], v[76:79]
	v_mfma_f32_16x16x32_bf16 v[72:75], v[136:139], v[168:171], v[72:75]
	v_mfma_f32_16x16x32_bf16 v[124:127], v[132:135], v[148:151], v[124:127]
	v_mfma_f32_16x16x32_bf16 v[120:123], v[140:143], v[148:151], v[120:123]
	v_mfma_f32_16x16x32_bf16 v[108:111], v[132:135], v[156:159], v[108:111]
	v_mfma_f32_16x16x32_bf16 v[104:107], v[140:143], v[156:159], v[104:107]
	v_mfma_f32_16x16x32_bf16 v[92:95], v[132:135], v[164:167], v[92:95]
	v_mfma_f32_16x16x32_bf16 v[88:91], v[140:143], v[164:167], v[88:91]
	v_mfma_f32_16x16x32_bf16 v[76:79], v[132:135], v[172:175], v[76:79]
	v_mfma_f32_16x16x32_bf16 v[72:75], v[140:143], v[172:175], v[72:75]
	s_barrier
	s_add_i32 s16, 0, 0x1c000
	s_add_i32 s17, s18, s23
	v_add_u32_e32 v188, s16, v245
	s_mov_b32 m0, s17
	ds_read_b128 v[176:179], v188
	ds_read_b128 v[180:183], v188 offset:1024
	ds_read_b128 v[184:187], v188 offset:2048
	ds_read_b128 v[188:191], v188 offset:3072
	global_load_lds_dwordx4 v194, s[80:81]
	s_add_i32 m0, s17, 0x2000
	s_nop 0
	global_load_lds_dwordx4 v206, s[80:81]
	s_barrier
; #define PG8_STAGE(bufoff, gbase, voff) do { _Pragma("unroll") for (int _i = 0; _i < 2; ++_i) \
;         __builtin_amdgcn_global_load_lds((const unsigned*)((const char*)(gbase) + (voff)[_i]), (LAS unsigned*)(lds + (bufoff) + ldsw + _i * 8192), 16, 0, 0); } while (0)
; #define PG8_LDA(dst, b, h) do { _Pragma("unroll") for (int m = 0; m < 4; ++m) _Pragma("unroll") for (int k = 0; k < 2; ++k) dst[m][k] = *(const LAS bf16x8*)(lds + PG8_SA(b, h) + aoff + m * 2048 + k * 1024); } while (0)
; #define PG8_LDB(dst, b, h) do { _Pragma("unroll") for (int n = 0; n < 2; ++n) _Pragma("unroll") for (int k = 0; k < 2; ++k) dst[n][k] = *(const LAS bf16x8*)(lds + PG8_SB(b, h) + boff + n * 2048 + k * 1024); } while (0)
; #define PG8_MMA(ai, bj, At, Bt) do { __builtin_amdgcn_s_setprio(1); _Pragma("unroll") for (int m = 0; m < 4; ++m) _Pragma("unroll") for (int n = 0; n < 2; ++n) _Pragma("unroll") for (int k = 0; k < 2; ++k) \
;         acc[ai][bj][m][n] = __builtin_amdgcn_mfma_f32_16x16x32_bf16(Bt[n][k], At[m][k], acc[ai][bj][m][n], 0, 0, 0); __builtin_amdgcn_s_setprio(0); } while (0)
; #define PG8_WAIT_V(n) asm volatile("s_waitcnt vmcnt(" #n ")" ::: "memory")
; #define PG8_WAIT_L(n) asm volatile("s_waitcnt lgkmcnt(" #n ")" ::: "memory")
; #define PG8_BAR __builtin_amdgcn_s_barrier()
; #define PG8_SCHED __builtin_amdgcn_sched_barrier(0)
; template <class Epi>
; __device__ __forceinline__ void gemm_phase(LAS unsigned char* lds, const Gemm g, const StaticOrder& S, const Epi& E) {
;     ...
;             PG8_LDB(B1, 1, 1); PG8_STAGE(PG8_SB(1, 0), b3, voffB);
;             PG8_BAR; PG8_WAIT_L(0); PG8_MMA(0, 1, At, B1); PG8_BAR;
;             PG8_LDA(At, 1, 1); PG8_STAGE(PG8_SA(1, 0), a3, voffA);
;             PG8_BAR; PG8_WAIT_L(0); PG8_MMA(1, 0, At, B0); PG8_BAR; PG8_SCHED;
;             PG8_STAGE(PG8_SB(1, 1), b3 + hstep, voffB);
;             PG8_WAIT_V(6); PG8_BAR; PG8_MMA(1, 1, At, B1); PG8_BAR;
	s_waitcnt lgkmcnt(0)
	s_waitcnt lgkmcnt(0)
	v_mfma_f32_16x16x32_bf16 v[116:119], v[176:179], v[144:147], v[116:119]
	v_mfma_f32_16x16x32_bf16 v[112:115], v[184:187], v[144:147], v[112:115]
	v_mfma_f32_16x16x32_bf16 v[100:103], v[176:179], v[152:155], v[100:103]
	v_mfma_f32_16x16x32_bf16 v[96:99], v[184:187], v[152:155], v[96:99]
	v_mfma_f32_16x16x32_bf16 v[84:87], v[176:179], v[160:163], v[84:87]
	v_mfma_f32_16x16x32_bf16 v[80:83], v[184:187], v[160:163], v[80:83]
	v_mfma_f32_16x16x32_bf16 v[68:71], v[176:179], v[168:171], v[68:71]
	v_mfma_f32_16x16x32_bf16 v[64:67], v[184:187], v[168:171], v[64:67]
	v_mfma_f32_16x16x32_bf16 v[116:119], v[180:183], v[148:151], v[116:119]
	v_mfma_f32_16x16x32_bf16 v[112:115], v[188:191], v[148:151], v[112:115]
	v_mfma_f32_16x16x32_bf16 v[100:103], v[180:183], v[156:159], v[100:103]
	v_mfma_f32_16x16x32_bf16 v[96:99], v[188:191], v[156:159], v[96:99]
	v_mfma_f32_16x16x32_bf16 v[84:87], v[180:183], v[164:167], v[84:87]
	v_mfma_f32_16x16x32_bf16 v[80:83], v[188:191], v[164:167], v[80:83]
	v_mfma_f32_16x16x32_bf16 v[68:71], v[180:183], v[172:175], v[68:71]
	v_mfma_f32_16x16x32_bf16 v[64:67], v[188:191], v[172:175], v[64:67]
	s_mov_b32 m0, s28
	s_barrier
	ds_read_b128 v[144:147], v247 offset:49152
	ds_read_b128 v[148:151], v247 offset:50176
	ds_read_b128 v[152:155], v247 offset:51200
	ds_read_b128 v[156:159], v247 offset:52224
	ds_read_b128 v[160:163], v247 offset:53248
	ds_read_b128 v[164:167], v247 offset:54272
	ds_read_b128 v[168:171], v247 offset:55296
	ds_read_b128 v[172:175], v247 offset:56320
	global_load_lds_dwordx4 v202, s[82:83]
	s_mov_b32 m0, s29
	s_nop 0
	global_load_lds_dwordx4 v204, s[82:83]
	s_barrier
	s_waitcnt lgkmcnt(0)
	s_waitcnt lgkmcnt(0)
	v_mfma_f32_16x16x32_bf16 v[60:63], v[128:131], v[144:147], v[60:63]
	v_mfma_f32_16x16x32_bf16 v[56:59], v[136:139], v[144:147], v[56:59]
	v_mfma_f32_16x16x32_bf16 v[44:47], v[128:131], v[152:155], v[44:47]
	v_mfma_f32_16x16x32_bf16 v[40:43], v[136:139], v[152:155], v[40:43]
	v_mfma_f32_16x16x32_bf16 v[28:31], v[128:131], v[160:163], v[28:31]
	v_mfma_f32_16x16x32_bf16 v[24:27], v[136:139], v[160:163], v[24:27]
	v_mfma_f32_16x16x32_bf16 v[12:15], v[128:131], v[168:171], v[12:15]
	v_mfma_f32_16x16x32_bf16 v[8:11], v[136:139], v[168:171], v[8:11]
	v_mfma_f32_16x16x32_bf16 v[60:63], v[132:135], v[148:151], v[60:63]
	v_mfma_f32_16x16x32_bf16 v[56:59], v[140:143], v[148:151], v[56:59]
	v_mfma_f32_16x16x32_bf16 v[44:47], v[132:135], v[156:159], v[44:47]
	v_mfma_f32_16x16x32_bf16 v[40:43], v[140:143], v[156:159], v[40:43]
	v_mfma_f32_16x16x32_bf16 v[28:31], v[132:135], v[164:167], v[28:31]
	v_mfma_f32_16x16x32_bf16 v[24:27], v[140:143], v[164:167], v[24:27]
	v_mfma_f32_16x16x32_bf16 v[12:15], v[132:135], v[172:175], v[12:15]
	v_mfma_f32_16x16x32_bf16 v[8:11], v[140:143], v[172:175], v[8:11]
	s_barrier
	s_add_i32 s16, s16, s23
	s_mov_b32 m0, s16
	s_nop 0
	global_load_lds_dwordx4 v194, s[84:85]
	s_add_i32 m0, s16, 0x2000
	s_nop 0
	global_load_lds_dwordx4 v206, s[84:85]
	s_waitcnt vmcnt(6)
	s_barrier
	v_mfma_f32_16x16x32_bf16 v[52:55], v[176:179], v[144:147], v[52:55]
	v_mfma_f32_16x16x32_bf16 v[48:51], v[184:187], v[144:147], v[48:51]
	v_mfma_f32_16x16x32_bf16 v[36:39], v[176:179], v[152:155], v[36:39]
	v_mfma_f32_16x16x32_bf16 v[32:35], v[184:187], v[152:155], v[32:35]
	v_mfma_f32_16x16x32_bf16 v[20:23], v[176:179], v[160:163], v[20:23]
	v_mfma_f32_16x16x32_bf16 v[16:19], v[184:187], v[160:163], v[16:19]
	v_mfma_f32_16x16x32_bf16 v[4:7], v[176:179], v[168:171], v[4:7]
	v_mfma_f32_16x16x32_bf16 v[0:3], v[184:187], v[168:171], v[0:3]
	v_mfma_f32_16x16x32_bf16 v[52:55], v[180:183], v[148:151], v[52:55]
	v_mfma_f32_16x16x32_bf16 v[48:51], v[188:191], v[148:151], v[48:51]
	v_mfma_f32_16x16x32_bf16 v[36:39], v[180:183], v[156:159], v[36:39]
	v_mfma_f32_16x16x32_bf16 v[32:35], v[188:191], v[156:159], v[32:35]
	v_mfma_f32_16x16x32_bf16 v[20:23], v[180:183], v[164:167], v[20:23]
	v_mfma_f32_16x16x32_bf16 v[16:19], v[188:191], v[164:167], v[16:19]
	v_mfma_f32_16x16x32_bf16 v[4:7], v[180:183], v[172:175], v[4:7]
	v_mfma_f32_16x16x32_bf16 v[0:3], v[188:191], v[172:175], v[0:3]
	s_add_u32 s39, s39, 0x100
	s_addc_u32 s40, s40, 0
	s_add_u32 s14, s14, 0x100
	s_addc_u32 s15, s15, 0
	s_cmp_ge_i32 s41, s30
	s_mov_b32 s16, s41
	s_barrier
	s_cbranch_scc0 .LBB0_119

; #define PG8_STAGE(bufoff, gbase, voff) do { _Pragma("unroll") for (int _i = 0; _i < 2; ++_i) \
;         __builtin_amdgcn_global_load_lds((const unsigned*)((const char*)(gbase) + (voff)[_i]), (LAS unsigned*)(lds + (bufoff) + ldsw + _i * 8192), 16, 0, 0); } while (0)
; #define PG8_LDA(dst, b, h) do { _Pragma("unroll") for (int m = 0; m < 4; ++m) _Pragma("unroll") for (int k = 0; k < 2; ++k) dst[m][k] = *(const LAS bf16x8*)(lds + PG8_SA(b, h) + aoff + m * 2048 + k * 1024); } while (0)
; #define PG8_LDB(dst, b, h) do { _Pragma("unroll") for (int n = 0; n < 2; ++n) _Pragma("unroll") for (int k = 0; k < 2; ++k) dst[n][k] = *(const LAS bf16x8*)(lds + PG8_SB(b, h) + boff + n * 2048 + k * 1024); } while (0)
; #define PG8_MMA(ai, bj, At, Bt) do { __builtin_amdgcn_s_setprio(1); _Pragma("unroll") for (int m = 0; m < 4; ++m) _Pragma("unroll") for (int n = 0; n < 2; ++n) _Pragma("unroll") for (int k = 0; k < 2; ++k) \
;         acc[ai][bj][m][n] = __builtin_amdgcn_mfma_f32_16x16x32_bf16(Bt[n][k], At[m][k], acc[ai][bj][m][n], 0, 0, 0); __builtin_amdgcn_s_setprio(0); } while (0)
; #define PG8_WAIT_V(n) asm volatile("s_waitcnt vmcnt(" #n ")" ::: "memory")
; #define PG8_WAIT_L(n) asm volatile("s_waitcnt lgkmcnt(" #n ")" ::: "memory")
; #define PG8_BAR __builtin_amdgcn_s_barrier()
; #define PG8_SCHED __builtin_amdgcn_sched_barrier(0)
; template <class Epi>
; __device__ __forceinline__ void gemm_phase(LAS unsigned char* lds, const Gemm g, const StaticOrder& S, const Epi& E) {
;     ...
;             PG8_LDB(B0, 0, 0); PG8_SCHED; PG8_LDA(At, 0, 0); PG8_STAGE(PG8_SA(1, 1), a1 + hstep, voffA);
;             PG8_WAIT_L(8); PG8_BAR; PG8_WAIT_L(0); PG8_MMA(0, 0, At, B0); PG8_BAR; PG8_SCHED;
;             PG8_LDB(B1, 0, 1); PG8_STAGE(PG8_SB(0, 0), b2, voffB);
;             PG8_BAR; PG8_WAIT_L(0); PG8_MMA(0, 1, At, B1); PG8_BAR;
;             PG8_LDA(At, 0, 1); PG8_STAGE(PG8_SA(0, 0), a2, voffA);
;             PG8_BAR; PG8_WAIT_L(0); PG8_MMA(1, 0, At, B0); PG8_BAR; PG8_SCHED;
;             PG8_STAGE(PG8_SB(0, 1), b2 + hstep, voffB);
;             PG8_WAIT_V(6); PG8_BAR; PG8_MMA(1, 1, At, B1); PG8_BAR;
.LBB0_165:
	s_add_i32 s44, s18, 2
	s_add_u32 s20, s16, 0x80
	s_addc_u32 s19, s17, 0
	s_add_i32 s45, 0, 0x10000
	v_add_u32_e32 v142, s45, v146
	ds_read_b128 v[138:141], v142
	ds_read_b128 v[152:155], v142 offset:1024
	ds_read_b128 v[156:159], v142 offset:2048
	ds_read_b128 v[160:163], v142 offset:3072
	s_cmp_eq_u32 s35, s18
	s_cselect_b32 s18, s10, s20
	s_cselect_b32 s19, s11, s19
	s_cselect_b32 s21, s13, s43
	s_cselect_b32 s20, s12, s42
	s_add_i32 m0, s27, 0xc000
	ds_read_b128 v[164:167], v150
	ds_read_b128 v[168:171], v150 offset:1024
	ds_read_b128 v[172:175], v150 offset:2048
	ds_read_b128 v[176:179], v150 offset:3072
	ds_read_b128 v[180:183], v150 offset:4096
	ds_read_b128 v[184:187], v150 offset:5120
	ds_read_b128 v[188:191], v150 offset:6144
	ds_read_b128 v[202:205], v150 offset:7168
	global_load_lds_dwordx4 v136, s[16:17]
	s_add_i32 m0, s27, 0xe000
	s_nop 0
	global_load_lds_dwordx4 v134, s[16:17]
	s_waitcnt lgkmcnt(8)
	s_barrier
	s_waitcnt lgkmcnt(0)
	s_waitcnt lgkmcnt(0)
	v_mfma_f32_16x16x32_bf16 v[124:127], v[138:141], v[164:167], v[124:127]
	v_mfma_f32_16x16x32_bf16 v[120:123], v[156:159], v[164:167], v[120:123]
	v_mfma_f32_16x16x32_bf16 v[108:111], v[138:141], v[172:175], v[108:111]
	v_mfma_f32_16x16x32_bf16 v[104:107], v[156:159], v[172:175], v[104:107]
	v_mfma_f32_16x16x32_bf16 v[92:95], v[138:141], v[180:183], v[92:95]
	v_mfma_f32_16x16x32_bf16 v[88:91], v[156:159], v[180:183], v[88:91]
	v_mfma_f32_16x16x32_bf16 v[76:79], v[138:141], v[188:191], v[76:79]
	v_mfma_f32_16x16x32_bf16 v[72:75], v[156:159], v[188:191], v[72:75]
	v_mfma_f32_16x16x32_bf16 v[124:127], v[152:155], v[168:171], v[124:127]
	v_mfma_f32_16x16x32_bf16 v[120:123], v[160:163], v[168:171], v[120:123]
	v_mfma_f32_16x16x32_bf16 v[108:111], v[152:155], v[176:179], v[108:111]
	v_mfma_f32_16x16x32_bf16 v[104:107], v[160:163], v[176:179], v[104:107]
	v_mfma_f32_16x16x32_bf16 v[92:95], v[152:155], v[184:187], v[92:95]
	v_mfma_f32_16x16x32_bf16 v[88:91], v[160:163], v[184:187], v[88:91]
	v_mfma_f32_16x16x32_bf16 v[76:79], v[152:155], v[202:205], v[76:79]
	v_mfma_f32_16x16x32_bf16 v[72:75], v[160:163], v[202:205], v[72:75]
	s_barrier
	s_add_i32 s46, 0, 0x14000
	v_add_u32_e32 v142, s46, v146
	s_add_i32 s45, s45, s26
	ds_read_b128 v[206:209], v142
	ds_read_b128 v[210:213], v142 offset:1024
	ds_read_b128 v[214:217], v142 offset:2048
	ds_read_b128 v[218:221], v142 offset:3072
	s_add_u32 s80, s20, 0x80
	s_addc_u32 s81, s21, 0
	s_mov_b32 m0, s45
	s_nop 0
	global_load_lds_dwordx4 v194, s[20:21]
	s_add_i32 m0, s45, 0x2000
	s_nop 0
	global_load_lds_dwordx4 v132, s[20:21]
	s_barrier
	s_waitcnt lgkmcnt(0)
	s_waitcnt lgkmcnt(0)
	v_mfma_f32_16x16x32_bf16 v[116:119], v[206:209], v[164:167], v[116:119]
	v_mfma_f32_16x16x32_bf16 v[112:115], v[214:217], v[164:167], v[112:115]
	v_mfma_f32_16x16x32_bf16 v[100:103], v[206:209], v[172:175], v[100:103]
	v_mfma_f32_16x16x32_bf16 v[96:99], v[214:217], v[172:175], v[96:99]
	v_mfma_f32_16x16x32_bf16 v[84:87], v[206:209], v[180:183], v[84:87]
	v_mfma_f32_16x16x32_bf16 v[80:83], v[214:217], v[180:183], v[80:83]
	v_mfma_f32_16x16x32_bf16 v[68:71], v[206:209], v[188:191], v[68:71]
	v_mfma_f32_16x16x32_bf16 v[64:67], v[214:217], v[188:191], v[64:67]
	v_mfma_f32_16x16x32_bf16 v[116:119], v[210:213], v[168:171], v[116:119]
	v_mfma_f32_16x16x32_bf16 v[112:115], v[218:221], v[168:171], v[112:115]
	v_mfma_f32_16x16x32_bf16 v[100:103], v[210:213], v[176:179], v[100:103]
	v_mfma_f32_16x16x32_bf16 v[96:99], v[218:221], v[176:179], v[96:99]
	v_mfma_f32_16x16x32_bf16 v[84:87], v[210:213], v[184:187], v[84:87]
	v_mfma_f32_16x16x32_bf16 v[80:83], v[218:221], v[184:187], v[80:83]
	v_mfma_f32_16x16x32_bf16 v[68:71], v[210:213], v[202:205], v[68:71]
	v_mfma_f32_16x16x32_bf16 v[64:67], v[218:221], v[202:205], v[64:67]
	s_mov_b32 m0, s27
	s_add_u32 s82, s18, 0x80
	s_addc_u32 s83, s19, 0
	s_barrier
	ds_read_b128 v[164:167], v150 offset:16384
	ds_read_b128 v[168:171], v150 offset:17408
	ds_read_b128 v[172:175], v150 offset:18432
	ds_read_b128 v[176:179], v150 offset:19456
	ds_read_b128 v[180:183], v150 offset:20480
	ds_read_b128 v[184:187], v150 offset:21504
	ds_read_b128 v[188:191], v150 offset:22528
	ds_read_b128 v[202:205], v150 offset:23552
	global_load_lds_dwordx4 v128, s[18:19]
	s_mov_b32 m0, s28
	s_nop 0
	global_load_lds_dwordx4 v130, s[18:19]
	s_barrier
	s_waitcnt lgkmcnt(0)
	s_waitcnt lgkmcnt(0)
	v_mfma_f32_16x16x32_bf16 v[60:63], v[138:141], v[164:167], v[60:63]
	v_mfma_f32_16x16x32_bf16 v[56:59], v[156:159], v[164:167], v[56:59]
	v_mfma_f32_16x16x32_bf16 v[44:47], v[138:141], v[172:175], v[44:47]
	v_mfma_f32_16x16x32_bf16 v[40:43], v[156:159], v[172:175], v[40:43]
	v_mfma_f32_16x16x32_bf16 v[28:31], v[138:141], v[180:183], v[28:31]
	v_mfma_f32_16x16x32_bf16 v[24:27], v[156:159], v[180:183], v[24:27]
	v_mfma_f32_16x16x32_bf16 v[12:15], v[138:141], v[188:191], v[12:15]
	v_mfma_f32_16x16x32_bf16 v[8:11], v[156:159], v[188:191], v[8:11]
	v_mfma_f32_16x16x32_bf16 v[60:63], v[152:155], v[168:171], v[60:63]
	v_mfma_f32_16x16x32_bf16 v[56:59], v[160:163], v[168:171], v[56:59]
	v_mfma_f32_16x16x32_bf16 v[44:47], v[152:155], v[176:179], v[44:47]
	v_mfma_f32_16x16x32_bf16 v[40:43], v[160:163], v[176:179], v[40:43]
	v_mfma_f32_16x16x32_bf16 v[28:31], v[152:155], v[184:187], v[28:31]
	v_mfma_f32_16x16x32_bf16 v[24:27], v[160:163], v[184:187], v[24:27]
	v_mfma_f32_16x16x32_bf16 v[12:15], v[152:155], v[202:205], v[12:15]
	v_mfma_f32_16x16x32_bf16 v[8:11], v[160:163], v[202:205], v[8:11]
	s_barrier
	s_add_u32 s20, s20, s2
	s_addc_u32 s21, s21, s3
	s_add_i32 s45, s46, s26
	s_add_u32 s84, s20, 0x80
	s_addc_u32 s85, s21, 0
	s_mov_b32 m0, s45
	s_nop 0
	global_load_lds_dwordx4 v194, s[20:21]
	s_add_i32 m0, s45, 0x2000
	s_nop 0
	global_load_lds_dwordx4 v132, s[20:21]
	s_waitcnt vmcnt(6)
	s_barrier
; #define PG8_STAGE(bufoff, gbase, voff) do { _Pragma("unroll") for (int _i = 0; _i < 2; ++_i) \
;         __builtin_amdgcn_global_load_lds((const unsigned*)((const char*)(gbase) + (voff)[_i]), (LAS unsigned*)(lds + (bufoff) + ldsw + _i * 8192), 16, 0, 0); } while (0)
; #define PG8_LDA(dst, b, h) do { _Pragma("unroll") for (int m = 0; m < 4; ++m) _Pragma("unroll") for (int k = 0; k < 2; ++k) dst[m][k] = *(const LAS bf16x8*)(lds + PG8_SA(b, h) + aoff + m * 2048 + k * 1024); } while (0)
; #define PG8_LDB(dst, b, h) do { _Pragma("unroll") for (int n = 0; n < 2; ++n) _Pragma("unroll") for (int k = 0; k < 2; ++k) dst[n][k] = *(const LAS bf16x8*)(lds + PG8_SB(b, h) + boff + n * 2048 + k * 1024); } while (0)
; #define PG8_MMA(ai, bj, At, Bt) do { __builtin_amdgcn_s_setprio(1); _Pragma("unroll") for (int m = 0; m < 4; ++m) _Pragma("unroll") for (int n = 0; n < 2; ++n) _Pragma("unroll") for (int k = 0; k < 2; ++k) \
;         acc[ai][bj][m][n] = __builtin_amdgcn_mfma_f32_16x16x32_bf16(Bt[n][k], At[m][k], acc[ai][bj][m][n], 0, 0, 0); __builtin_amdgcn_s_setprio(0); } while (0)
; #define PG8_WAIT_V(n) asm volatile("s_waitcnt vmcnt(" #n ")" ::: "memory")
; #define PG8_WAIT_L(n) asm volatile("s_waitcnt lgkmcnt(" #n ")" ::: "memory")
; #define PG8_BAR __builtin_amdgcn_s_barrier()
; #define PG8_SCHED __builtin_amdgcn_sched_barrier(0)
; template <class Epi>
; __device__ __forceinline__ void gemm_phase(LAS unsigned char* lds, const Gemm g, const StaticOrder& S, const Epi& E) {
;     ...
;             PG8_WAIT_V(6); PG8_BAR; PG8_MMA(1, 1, At, B1); PG8_BAR;
;             PG8_LDB(B0, 1, 0); PG8_SCHED; PG8_LDA(At, 1, 0); PG8_STAGE(PG8_SA(0, 1), a2 + hstep, voffA);
;             PG8_WAIT_L(8); PG8_BAR; PG8_WAIT_L(0); PG8_MMA(0, 0, At, B0); PG8_BAR; PG8_SCHED;
;             PG8_LDB(B1, 1, 1); PG8_STAGE(PG8_SB(1, 0), b3, voffB);
;             PG8_BAR; PG8_WAIT_L(0); PG8_MMA(0, 1, At, B1); PG8_BAR;
;             PG8_LDA(At, 1, 1); PG8_STAGE(PG8_SA(1, 0), a3, voffA);
;             PG8_BAR; PG8_WAIT_L(0); PG8_MMA(1, 0, At, B0); PG8_BAR; PG8_SCHED;
;             PG8_STAGE(PG8_SB(1, 1), b3 + hstep, voffB);
	v_mfma_f32_16x16x32_bf16 v[52:55], v[206:209], v[164:167], v[52:55]
	v_mfma_f32_16x16x32_bf16 v[48:51], v[214:217], v[164:167], v[48:51]
	v_mfma_f32_16x16x32_bf16 v[36:39], v[206:209], v[172:175], v[36:39]
	v_mfma_f32_16x16x32_bf16 v[32:35], v[214:217], v[172:175], v[32:35]
	v_mfma_f32_16x16x32_bf16 v[20:23], v[206:209], v[180:183], v[20:23]
	v_mfma_f32_16x16x32_bf16 v[16:19], v[214:217], v[180:183], v[16:19]
	v_mfma_f32_16x16x32_bf16 v[4:7], v[206:209], v[188:191], v[4:7]
	v_mfma_f32_16x16x32_bf16 v[0:3], v[214:217], v[188:191], v[0:3]
	v_mfma_f32_16x16x32_bf16 v[52:55], v[210:213], v[168:171], v[52:55]
	v_mfma_f32_16x16x32_bf16 v[48:51], v[218:221], v[168:171], v[48:51]
	v_mfma_f32_16x16x32_bf16 v[36:39], v[210:213], v[176:179], v[36:39]
	v_mfma_f32_16x16x32_bf16 v[32:35], v[218:221], v[176:179], v[32:35]
	v_mfma_f32_16x16x32_bf16 v[20:23], v[210:213], v[184:187], v[20:23]
	v_mfma_f32_16x16x32_bf16 v[16:19], v[218:221], v[184:187], v[16:19]
	v_mfma_f32_16x16x32_bf16 v[4:7], v[210:213], v[202:205], v[4:7]
	v_mfma_f32_16x16x32_bf16 v[0:3], v[218:221], v[202:205], v[0:3]
	s_add_i32 s20, 0, 0x18000
	v_add_u32_e32 v151, s20, v146
	s_barrier
	ds_read_b128 v[138:141], v151
	ds_read_b128 v[152:155], v151 offset:1024
	ds_read_b128 v[156:159], v151 offset:2048
	ds_read_b128 v[160:163], v151 offset:3072
	s_add_u32 s18, s18, s2
	s_addc_u32 s19, s19, s3
	s_mov_b32 m0, s29
	ds_read_b128 v[164:167], v150 offset:32768
	ds_read_b128 v[168:171], v150 offset:33792
	ds_read_b128 v[172:175], v150 offset:34816
	ds_read_b128 v[176:179], v150 offset:35840
	ds_read_b128 v[180:183], v150 offset:36864
	ds_read_b128 v[184:187], v150 offset:37888
	ds_read_b128 v[188:191], v150 offset:38912
	ds_read_b128 v[202:205], v150 offset:39936
	global_load_lds_dwordx4 v128, s[18:19]
	s_mov_b32 m0, s30
	s_nop 0
	global_load_lds_dwordx4 v130, s[18:19]
	s_waitcnt lgkmcnt(8)
	s_barrier
	s_waitcnt lgkmcnt(0)
	s_waitcnt lgkmcnt(0)
	v_mfma_f32_16x16x32_bf16 v[124:127], v[138:141], v[164:167], v[124:127]
	v_mfma_f32_16x16x32_bf16 v[120:123], v[156:159], v[164:167], v[120:123]
	v_mfma_f32_16x16x32_bf16 v[108:111], v[138:141], v[172:175], v[108:111]
	v_mfma_f32_16x16x32_bf16 v[104:107], v[156:159], v[172:175], v[104:107]
	v_mfma_f32_16x16x32_bf16 v[92:95], v[138:141], v[180:183], v[92:95]
	v_mfma_f32_16x16x32_bf16 v[88:91], v[156:159], v[180:183], v[88:91]
	v_mfma_f32_16x16x32_bf16 v[76:79], v[138:141], v[188:191], v[76:79]
	v_mfma_f32_16x16x32_bf16 v[72:75], v[156:159], v[188:191], v[72:75]
	v_mfma_f32_16x16x32_bf16 v[124:127], v[152:155], v[168:171], v[124:127]
	v_mfma_f32_16x16x32_bf16 v[120:123], v[160:163], v[168:171], v[120:123]
	v_mfma_f32_16x16x32_bf16 v[108:111], v[152:155], v[176:179], v[108:111]
	v_mfma_f32_16x16x32_bf16 v[104:107], v[160:163], v[176:179], v[104:107]
	v_mfma_f32_16x16x32_bf16 v[92:95], v[152:155], v[184:187], v[92:95]
	v_mfma_f32_16x16x32_bf16 v[88:91], v[160:163], v[184:187], v[88:91]
	v_mfma_f32_16x16x32_bf16 v[76:79], v[152:155], v[202:205], v[76:79]
	v_mfma_f32_16x16x32_bf16 v[72:75], v[160:163], v[202:205], v[72:75]
	s_barrier
	s_add_i32 s18, 0, 0x1c000
	s_add_i32 s19, s20, s26
	v_add_u32_e32 v151, s18, v146
	s_mov_b32 m0, s19
	ds_read_b128 v[206:209], v151
	ds_read_b128 v[210:213], v151 offset:1024
	ds_read_b128 v[214:217], v151 offset:2048
	ds_read_b128 v[218:221], v151 offset:3072
	global_load_lds_dwordx4 v194, s[80:81]
	s_add_i32 m0, s19, 0x2000
	s_nop 0
	global_load_lds_dwordx4 v132, s[80:81]
	s_barrier
; #define PG8_STAGE(bufoff, gbase, voff) do { _Pragma("unroll") for (int _i = 0; _i < 2; ++_i) \
;         __builtin_amdgcn_global_load_lds((const unsigned*)((const char*)(gbase) + (voff)[_i]), (LAS unsigned*)(lds + (bufoff) + ldsw + _i * 8192), 16, 0, 0); } while (0)
; #define PG8_LDA(dst, b, h) do { _Pragma("unroll") for (int m = 0; m < 4; ++m) _Pragma("unroll") for (int k = 0; k < 2; ++k) dst[m][k] = *(const LAS bf16x8*)(lds + PG8_SA(b, h) + aoff + m * 2048 + k * 1024); } while (0)
; #define PG8_LDB(dst, b, h) do { _Pragma("unroll") for (int n = 0; n < 2; ++n) _Pragma("unroll") for (int k = 0; k < 2; ++k) dst[n][k] = *(const LAS bf16x8*)(lds + PG8_SB(b, h) + boff + n * 2048 + k * 1024); } while (0)
; #define PG8_MMA(ai, bj, At, Bt) do { __builtin_amdgcn_s_setprio(1); _Pragma("unroll") for (int m = 0; m < 4; ++m) _Pragma("unroll") for (int n = 0; n < 2; ++n) _Pragma("unroll") for (int k = 0; k < 2; ++k) \
;         acc[ai][bj][m][n] = __builtin_amdgcn_mfma_f32_16x16x32_bf16(Bt[n][k], At[m][k], acc[ai][bj][m][n], 0, 0, 0); __builtin_amdgcn_s_setprio(0); } while (0)
; #define PG8_WAIT_V(n) asm volatile("s_waitcnt vmcnt(" #n ")" ::: "memory")
; #define PG8_WAIT_L(n) asm volatile("s_waitcnt lgkmcnt(" #n ")" ::: "memory")
; #define PG8_BAR __builtin_amdgcn_s_barrier()
; #define PG8_SCHED __builtin_amdgcn_sched_barrier(0)
; template <class Epi>
; __device__ __forceinline__ void gemm_phase(LAS unsigned char* lds, const Gemm g, const StaticOrder& S, const Epi& E) {
;     ...
;             PG8_LDB(B1, 1, 1); PG8_STAGE(PG8_SB(1, 0), b3, voffB);
;             PG8_BAR; PG8_WAIT_L(0); PG8_MMA(0, 1, At, B1); PG8_BAR;
;             PG8_LDA(At, 1, 1); PG8_STAGE(PG8_SA(1, 0), a3, voffA);
;             PG8_BAR; PG8_WAIT_L(0); PG8_MMA(1, 0, At, B0); PG8_BAR; PG8_SCHED;
;             PG8_STAGE(PG8_SB(1, 1), b3 + hstep, voffB);
;             PG8_WAIT_V(6); PG8_BAR; PG8_MMA(1, 1, At, B1); PG8_BAR;
	s_waitcnt lgkmcnt(0)
	s_waitcnt lgkmcnt(0)
	v_mfma_f32_16x16x32_bf16 v[116:119], v[206:209], v[164:167], v[116:119]
	v_mfma_f32_16x16x32_bf16 v[112:115], v[214:217], v[164:167], v[112:115]
	v_mfma_f32_16x16x32_bf16 v[100:103], v[206:209], v[172:175], v[100:103]
	v_mfma_f32_16x16x32_bf16 v[96:99], v[214:217], v[172:175], v[96:99]
	v_mfma_f32_16x16x32_bf16 v[84:87], v[206:209], v[180:183], v[84:87]
	v_mfma_f32_16x16x32_bf16 v[80:83], v[214:217], v[180:183], v[80:83]
	v_mfma_f32_16x16x32_bf16 v[68:71], v[206:209], v[188:191], v[68:71]
	v_mfma_f32_16x16x32_bf16 v[64:67], v[214:217], v[188:191], v[64:67]
	v_mfma_f32_16x16x32_bf16 v[116:119], v[210:213], v[168:171], v[116:119]
	v_mfma_f32_16x16x32_bf16 v[112:115], v[218:221], v[168:171], v[112:115]
	v_mfma_f32_16x16x32_bf16 v[100:103], v[210:213], v[176:179], v[100:103]
	v_mfma_f32_16x16x32_bf16 v[96:99], v[218:221], v[176:179], v[96:99]
	v_mfma_f32_16x16x32_bf16 v[84:87], v[210:213], v[184:187], v[84:87]
	v_mfma_f32_16x16x32_bf16 v[80:83], v[218:221], v[184:187], v[80:83]
	v_mfma_f32_16x16x32_bf16 v[68:71], v[210:213], v[202:205], v[68:71]
	v_mfma_f32_16x16x32_bf16 v[64:67], v[218:221], v[202:205], v[64:67]
	s_mov_b32 m0, s31
	s_barrier
	ds_read_b128 v[164:167], v150 offset:49152
	ds_read_b128 v[168:171], v150 offset:50176
	ds_read_b128 v[172:175], v150 offset:51200
	ds_read_b128 v[176:179], v150 offset:52224
	ds_read_b128 v[180:183], v150 offset:53248
	ds_read_b128 v[184:187], v150 offset:54272
	ds_read_b128 v[188:191], v150 offset:55296
	ds_read_b128 v[202:205], v150 offset:56320
	global_load_lds_dwordx4 v128, s[82:83]
	s_mov_b32 m0, s33
	s_nop 0
	global_load_lds_dwordx4 v130, s[82:83]
	s_barrier
	s_waitcnt lgkmcnt(0)
	s_waitcnt lgkmcnt(0)
	v_mfma_f32_16x16x32_bf16 v[60:63], v[138:141], v[164:167], v[60:63]
	v_mfma_f32_16x16x32_bf16 v[56:59], v[156:159], v[164:167], v[56:59]
	v_mfma_f32_16x16x32_bf16 v[44:47], v[138:141], v[172:175], v[44:47]
	v_mfma_f32_16x16x32_bf16 v[40:43], v[156:159], v[172:175], v[40:43]
	v_mfma_f32_16x16x32_bf16 v[28:31], v[138:141], v[180:183], v[28:31]
	v_mfma_f32_16x16x32_bf16 v[24:27], v[156:159], v[180:183], v[24:27]
	v_mfma_f32_16x16x32_bf16 v[12:15], v[138:141], v[188:191], v[12:15]
	v_mfma_f32_16x16x32_bf16 v[8:11], v[156:159], v[188:191], v[8:11]
	v_mfma_f32_16x16x32_bf16 v[60:63], v[152:155], v[168:171], v[60:63]
	v_mfma_f32_16x16x32_bf16 v[56:59], v[160:163], v[168:171], v[56:59]
	v_mfma_f32_16x16x32_bf16 v[44:47], v[152:155], v[176:179], v[44:47]
	v_mfma_f32_16x16x32_bf16 v[40:43], v[160:163], v[176:179], v[40:43]
	v_mfma_f32_16x16x32_bf16 v[28:31], v[152:155], v[184:187], v[28:31]
	v_mfma_f32_16x16x32_bf16 v[24:27], v[160:163], v[184:187], v[24:27]
	v_mfma_f32_16x16x32_bf16 v[12:15], v[152:155], v[202:205], v[12:15]
	v_mfma_f32_16x16x32_bf16 v[8:11], v[160:163], v[202:205], v[8:11]
	s_barrier
	s_add_i32 s18, s18, s26
	s_mov_b32 m0, s18
	s_nop 0
	global_load_lds_dwordx4 v194, s[84:85]
	s_add_i32 m0, s18, 0x2000
	s_nop 0
	global_load_lds_dwordx4 v132, s[84:85]
	s_waitcnt vmcnt(6)
	s_barrier
	v_mfma_f32_16x16x32_bf16 v[52:55], v[206:209], v[164:167], v[52:55]
	v_mfma_f32_16x16x32_bf16 v[48:51], v[214:217], v[164:167], v[48:51]
	v_mfma_f32_16x16x32_bf16 v[36:39], v[206:209], v[172:175], v[36:39]
	v_mfma_f32_16x16x32_bf16 v[32:35], v[214:217], v[172:175], v[32:35]
	v_mfma_f32_16x16x32_bf16 v[20:23], v[206:209], v[180:183], v[20:23]
	v_mfma_f32_16x16x32_bf16 v[16:19], v[214:217], v[180:183], v[16:19]
	v_mfma_f32_16x16x32_bf16 v[4:7], v[206:209], v[188:191], v[4:7]
	v_mfma_f32_16x16x32_bf16 v[0:3], v[214:217], v[188:191], v[0:3]
	v_mfma_f32_16x16x32_bf16 v[52:55], v[210:213], v[168:171], v[52:55]
	v_mfma_f32_16x16x32_bf16 v[48:51], v[218:221], v[168:171], v[48:51]
	v_mfma_f32_16x16x32_bf16 v[36:39], v[210:213], v[176:179], v[36:39]
	v_mfma_f32_16x16x32_bf16 v[32:35], v[218:221], v[176:179], v[32:35]
	v_mfma_f32_16x16x32_bf16 v[20:23], v[210:213], v[184:187], v[20:23]
	v_mfma_f32_16x16x32_bf16 v[16:19], v[218:221], v[184:187], v[16:19]
	v_mfma_f32_16x16x32_bf16 v[4:7], v[210:213], v[202:205], v[4:7]
	v_mfma_f32_16x16x32_bf16 v[0:3], v[218:221], v[202:205], v[0:3]
	s_add_u32 s42, s42, 0x100
	s_addc_u32 s43, s43, 0
	s_add_u32 s16, s16, 0x100
	s_addc_u32 s17, s17, 0
	s_cmp_ge_i32 s44, s34
	s_mov_b32 s18, s44
	s_barrier
	s_cbranch_scc0 .LBB0_165

; #define PG8_STAGE(bufoff, gbase, voff) do { _Pragma("unroll") for (int _i = 0; _i < 2; ++_i) \
;         __builtin_amdgcn_global_load_lds((const unsigned*)((const char*)(gbase) + (voff)[_i]), (LAS unsigned*)(lds + (bufoff) + ldsw + _i * 8192), 16, 0, 0); } while (0)
; #define PG8_LDA(dst, b, h) do { _Pragma("unroll") for (int m = 0; m < 4; ++m) _Pragma("unroll") for (int k = 0; k < 2; ++k) dst[m][k] = *(const LAS bf16x8*)(lds + PG8_SA(b, h) + aoff + m * 2048 + k * 1024); } while (0)
; #define PG8_LDB(dst, b, h) do { _Pragma("unroll") for (int n = 0; n < 2; ++n) _Pragma("unroll") for (int k = 0; k < 2; ++k) dst[n][k] = *(const LAS bf16x8*)(lds + PG8_SB(b, h) + boff + n * 2048 + k * 1024); } while (0)
; #define PG8_MMA(ai, bj, At, Bt) do { __builtin_amdgcn_s_setprio(1); _Pragma("unroll") for (int m = 0; m < 4; ++m) _Pragma("unroll") for (int n = 0; n < 2; ++n) _Pragma("unroll") for (int k = 0; k < 2; ++k) \
;         acc[ai][bj][m][n] = __builtin_amdgcn_mfma_f32_16x16x32_bf16(Bt[n][k], At[m][k], acc[ai][bj][m][n], 0, 0, 0); __builtin_amdgcn_s_setprio(0); } while (0)
; #define PG8_WAIT_V(n) asm volatile("s_waitcnt vmcnt(" #n ")" ::: "memory")
; #define PG8_WAIT_L(n) asm volatile("s_waitcnt lgkmcnt(" #n ")" ::: "memory")
; #define PG8_BAR __builtin_amdgcn_s_barrier()
; #define PG8_SCHED __builtin_amdgcn_sched_barrier(0)
; template <class Epi>
; __device__ __forceinline__ void gemm_phase(LAS unsigned char* lds, const Gemm g, const StaticOrder& S, const Epi& E) {
;     ...
;             PG8_LDB(B0, 0, 0); PG8_SCHED; PG8_LDA(At, 0, 0); PG8_STAGE(PG8_SA(1, 1), a1 + hstep, voffA);
;             PG8_WAIT_L(8); PG8_BAR; PG8_WAIT_L(0); PG8_MMA(0, 0, At, B0); PG8_BAR; PG8_SCHED;
;             PG8_LDB(B1, 0, 1); PG8_STAGE(PG8_SB(0, 0), b2, voffB);
;             PG8_BAR; PG8_WAIT_L(0); PG8_MMA(0, 1, At, B1); PG8_BAR;
;             PG8_LDA(At, 0, 1); PG8_STAGE(PG8_SA(0, 0), a2, voffA);
;             PG8_BAR; PG8_WAIT_L(0); PG8_MMA(1, 0, At, B0); PG8_BAR; PG8_SCHED;
;             PG8_STAGE(PG8_SB(0, 1), b2 + hstep, voffB);
;             PG8_WAIT_V(6); PG8_BAR; PG8_MMA(1, 1, At, B1); PG8_BAR;
.LBB0_528:
	s_add_i32 s42, s18, 2
	s_add_u32 s20, s16, 0x80
	s_addc_u32 s19, s17, 0
	s_add_i32 s43, 0, 0x10000
	v_add_u32_e32 v149, s43, v144
	ds_read_b128 v[138:141], v149
	ds_read_b128 v[150:153], v149 offset:1024
	ds_read_b128 v[154:157], v149 offset:2048
	ds_read_b128 v[158:161], v149 offset:3072
	s_cmp_eq_u32 s33, s18
	s_cselect_b32 s18, s10, s20
	s_cselect_b32 s19, s11, s19
	s_cselect_b32 s21, s13, s41
	s_cselect_b32 s20, s12, s40
	s_add_i32 m0, s25, 0xc000
	ds_read_b128 v[162:165], v148
	ds_read_b128 v[166:169], v148 offset:1024
	ds_read_b128 v[170:173], v148 offset:2048
	ds_read_b128 v[174:177], v148 offset:3072
	ds_read_b128 v[178:181], v148 offset:4096
	ds_read_b128 v[182:185], v148 offset:5120
	ds_read_b128 v[186:189], v148 offset:6144
	ds_read_b128 v[202:205], v148 offset:7168
	global_load_lds_dwordx4 v136, s[16:17]
	s_add_i32 m0, s25, 0xe000
	s_nop 0
	global_load_lds_dwordx4 v134, s[16:17]
	s_waitcnt lgkmcnt(8)
	s_barrier
	s_waitcnt lgkmcnt(0)
	s_waitcnt lgkmcnt(0)
	v_mfma_f32_16x16x32_bf16 v[124:127], v[138:141], v[162:165], v[124:127]
	v_mfma_f32_16x16x32_bf16 v[120:123], v[154:157], v[162:165], v[120:123]
	v_mfma_f32_16x16x32_bf16 v[108:111], v[138:141], v[170:173], v[108:111]
	v_mfma_f32_16x16x32_bf16 v[104:107], v[154:157], v[170:173], v[104:107]
	v_mfma_f32_16x16x32_bf16 v[92:95], v[138:141], v[178:181], v[92:95]
	v_mfma_f32_16x16x32_bf16 v[88:91], v[154:157], v[178:181], v[88:91]
	v_mfma_f32_16x16x32_bf16 v[76:79], v[138:141], v[186:189], v[76:79]
	v_mfma_f32_16x16x32_bf16 v[72:75], v[154:157], v[186:189], v[72:75]
	v_mfma_f32_16x16x32_bf16 v[124:127], v[150:153], v[166:169], v[124:127]
	v_mfma_f32_16x16x32_bf16 v[120:123], v[158:161], v[166:169], v[120:123]
	v_mfma_f32_16x16x32_bf16 v[108:111], v[150:153], v[174:177], v[108:111]
	v_mfma_f32_16x16x32_bf16 v[104:107], v[158:161], v[174:177], v[104:107]
	v_mfma_f32_16x16x32_bf16 v[92:95], v[150:153], v[182:185], v[92:95]
	v_mfma_f32_16x16x32_bf16 v[88:91], v[158:161], v[182:185], v[88:91]
	v_mfma_f32_16x16x32_bf16 v[76:79], v[150:153], v[202:205], v[76:79]
	v_mfma_f32_16x16x32_bf16 v[72:75], v[158:161], v[202:205], v[72:75]
	s_barrier
	s_add_i32 s44, 0, 0x14000
	s_add_i32 s43, s43, s24
	v_add_u32_e32 v149, s44, v144
	s_add_u32 s80, s20, 0x80
	s_addc_u32 s81, s21, 0
	s_mov_b32 m0, s43
	ds_read_b128 v[206:209], v149
	ds_read_b128 v[210:213], v149 offset:1024
	ds_read_b128 v[214:217], v149 offset:2048
	ds_read_b128 v[218:221], v149 offset:3072
	global_load_lds_dwordx4 v194, s[20:21]
	s_add_i32 m0, s43, 0x2000
	s_nop 0
	global_load_lds_dwordx4 v132, s[20:21]
	s_barrier
	s_waitcnt lgkmcnt(0)
	s_waitcnt lgkmcnt(0)
	v_mfma_f32_16x16x32_bf16 v[116:119], v[206:209], v[162:165], v[116:119]
	v_mfma_f32_16x16x32_bf16 v[112:115], v[214:217], v[162:165], v[112:115]
	v_mfma_f32_16x16x32_bf16 v[100:103], v[206:209], v[170:173], v[100:103]
	v_mfma_f32_16x16x32_bf16 v[96:99], v[214:217], v[170:173], v[96:99]
	v_mfma_f32_16x16x32_bf16 v[84:87], v[206:209], v[178:181], v[84:87]
	v_mfma_f32_16x16x32_bf16 v[80:83], v[214:217], v[178:181], v[80:83]
	v_mfma_f32_16x16x32_bf16 v[68:71], v[206:209], v[186:189], v[68:71]
	v_mfma_f32_16x16x32_bf16 v[64:67], v[214:217], v[186:189], v[64:67]
	v_mfma_f32_16x16x32_bf16 v[116:119], v[210:213], v[166:169], v[116:119]
	v_mfma_f32_16x16x32_bf16 v[112:115], v[218:221], v[166:169], v[112:115]
	v_mfma_f32_16x16x32_bf16 v[100:103], v[210:213], v[174:177], v[100:103]
	v_mfma_f32_16x16x32_bf16 v[96:99], v[218:221], v[174:177], v[96:99]
	v_mfma_f32_16x16x32_bf16 v[84:87], v[210:213], v[182:185], v[84:87]
	v_mfma_f32_16x16x32_bf16 v[80:83], v[218:221], v[182:185], v[80:83]
	v_mfma_f32_16x16x32_bf16 v[68:71], v[210:213], v[202:205], v[68:71]
	v_mfma_f32_16x16x32_bf16 v[64:67], v[218:221], v[202:205], v[64:67]
	s_mov_b32 m0, s25
	s_add_u32 s82, s18, 0x80
	s_addc_u32 s83, s19, 0
	s_barrier
	ds_read_b128 v[162:165], v148 offset:16384
	ds_read_b128 v[166:169], v148 offset:17408
	ds_read_b128 v[170:173], v148 offset:18432
	ds_read_b128 v[174:177], v148 offset:19456
	ds_read_b128 v[178:181], v148 offset:20480
	ds_read_b128 v[182:185], v148 offset:21504
	ds_read_b128 v[186:189], v148 offset:22528
	ds_read_b128 v[202:205], v148 offset:23552
	global_load_lds_dwordx4 v128, s[18:19]
	s_mov_b32 m0, s26
	s_nop 0
	global_load_lds_dwordx4 v130, s[18:19]
	s_barrier
	s_waitcnt lgkmcnt(0)
	s_waitcnt lgkmcnt(0)
	v_mfma_f32_16x16x32_bf16 v[60:63], v[138:141], v[162:165], v[60:63]
	v_mfma_f32_16x16x32_bf16 v[56:59], v[154:157], v[162:165], v[56:59]
	v_mfma_f32_16x16x32_bf16 v[44:47], v[138:141], v[170:173], v[44:47]
	v_mfma_f32_16x16x32_bf16 v[40:43], v[154:157], v[170:173], v[40:43]
	v_mfma_f32_16x16x32_bf16 v[28:31], v[138:141], v[178:181], v[28:31]
	v_mfma_f32_16x16x32_bf16 v[24:27], v[154:157], v[178:181], v[24:27]
	v_mfma_f32_16x16x32_bf16 v[12:15], v[138:141], v[186:189], v[12:15]
	v_mfma_f32_16x16x32_bf16 v[8:11], v[154:157], v[186:189], v[8:11]
	v_mfma_f32_16x16x32_bf16 v[60:63], v[150:153], v[166:169], v[60:63]
	v_mfma_f32_16x16x32_bf16 v[56:59], v[158:161], v[166:169], v[56:59]
	v_mfma_f32_16x16x32_bf16 v[44:47], v[150:153], v[174:177], v[44:47]
	v_mfma_f32_16x16x32_bf16 v[40:43], v[158:161], v[174:177], v[40:43]
	v_mfma_f32_16x16x32_bf16 v[28:31], v[150:153], v[182:185], v[28:31]
	v_mfma_f32_16x16x32_bf16 v[24:27], v[158:161], v[182:185], v[24:27]
	v_mfma_f32_16x16x32_bf16 v[12:15], v[150:153], v[202:205], v[12:15]
	v_mfma_f32_16x16x32_bf16 v[8:11], v[158:161], v[202:205], v[8:11]
	s_barrier
	s_add_u32 s20, s20, s2
	s_addc_u32 s21, s21, s3
	s_add_i32 s43, s44, s24
	s_add_u32 s84, s20, 0x80
	s_addc_u32 s85, s21, 0
	s_mov_b32 m0, s43
	s_nop 0
	global_load_lds_dwordx4 v194, s[20:21]
	s_add_i32 m0, s43, 0x2000
	s_nop 0
	global_load_lds_dwordx4 v132, s[20:21]
	s_waitcnt vmcnt(6)
	s_barrier
; #define PG8_STAGE(bufoff, gbase, voff) do { _Pragma("unroll") for (int _i = 0; _i < 2; ++_i) \
;         __builtin_amdgcn_global_load_lds((const unsigned*)((const char*)(gbase) + (voff)[_i]), (LAS unsigned*)(lds + (bufoff) + ldsw + _i * 8192), 16, 0, 0); } while (0)
; #define PG8_LDA(dst, b, h) do { _Pragma("unroll") for (int m = 0; m < 4; ++m) _Pragma("unroll") for (int k = 0; k < 2; ++k) dst[m][k] = *(const LAS bf16x8*)(lds + PG8_SA(b, h) + aoff + m * 2048 + k * 1024); } while (0)
; #define PG8_LDB(dst, b, h) do { _Pragma("unroll") for (int n = 0; n < 2; ++n) _Pragma("unroll") for (int k = 0; k < 2; ++k) dst[n][k] = *(const LAS bf16x8*)(lds + PG8_SB(b, h) + boff + n * 2048 + k * 1024); } while (0)
; #define PG8_MMA(ai, bj, At, Bt) do { __builtin_amdgcn_s_setprio(1); _Pragma("unroll") for (int m = 0; m < 4; ++m) _Pragma("unroll") for (int n = 0; n < 2; ++n) _Pragma("unroll") for (int k = 0; k < 2; ++k) \
;         acc[ai][bj][m][n] = __builtin_amdgcn_mfma_f32_16x16x32_bf16(Bt[n][k], At[m][k], acc[ai][bj][m][n], 0, 0, 0); __builtin_amdgcn_s_setprio(0); } while (0)
; #define PG8_WAIT_V(n) asm volatile("s_waitcnt vmcnt(" #n ")" ::: "memory")
; #define PG8_WAIT_L(n) asm volatile("s_waitcnt lgkmcnt(" #n ")" ::: "memory")
; #define PG8_BAR __builtin_amdgcn_s_barrier()
; #define PG8_SCHED __builtin_amdgcn_sched_barrier(0)
; template <class Epi>
; __device__ __forceinline__ void gemm_phase(LAS unsigned char* lds, const Gemm g, const StaticOrder& S, const Epi& E) {
;     ...
;             PG8_WAIT_V(6); PG8_BAR; PG8_MMA(1, 1, At, B1); PG8_BAR;
;             PG8_LDB(B0, 1, 0); PG8_SCHED; PG8_LDA(At, 1, 0); PG8_STAGE(PG8_SA(0, 1), a2 + hstep, voffA);
;             PG8_WAIT_L(8); PG8_BAR; PG8_WAIT_L(0); PG8_MMA(0, 0, At, B0); PG8_BAR; PG8_SCHED;
;             PG8_LDB(B1, 1, 1); PG8_STAGE(PG8_SB(1, 0), b3, voffB);
;             PG8_BAR; PG8_WAIT_L(0); PG8_MMA(0, 1, At, B1); PG8_BAR;
;             PG8_LDA(At, 1, 1); PG8_STAGE(PG8_SA(1, 0), a3, voffA);
;             PG8_BAR; PG8_WAIT_L(0); PG8_MMA(1, 0, At, B0); PG8_BAR; PG8_SCHED;
;             PG8_STAGE(PG8_SB(1, 1), b3 + hstep, voffB);
	v_mfma_f32_16x16x32_bf16 v[52:55], v[206:209], v[162:165], v[52:55]
	v_mfma_f32_16x16x32_bf16 v[48:51], v[214:217], v[162:165], v[48:51]
	v_mfma_f32_16x16x32_bf16 v[36:39], v[206:209], v[170:173], v[36:39]
	v_mfma_f32_16x16x32_bf16 v[32:35], v[214:217], v[170:173], v[32:35]
	v_mfma_f32_16x16x32_bf16 v[20:23], v[206:209], v[178:181], v[20:23]
	v_mfma_f32_16x16x32_bf16 v[16:19], v[214:217], v[178:181], v[16:19]
	v_mfma_f32_16x16x32_bf16 v[4:7], v[206:209], v[186:189], v[4:7]
	v_mfma_f32_16x16x32_bf16 v[0:3], v[214:217], v[186:189], v[0:3]
	v_mfma_f32_16x16x32_bf16 v[52:55], v[210:213], v[166:169], v[52:55]
	v_mfma_f32_16x16x32_bf16 v[48:51], v[218:221], v[166:169], v[48:51]
	v_mfma_f32_16x16x32_bf16 v[36:39], v[210:213], v[174:177], v[36:39]
	v_mfma_f32_16x16x32_bf16 v[32:35], v[218:221], v[174:177], v[32:35]
	v_mfma_f32_16x16x32_bf16 v[20:23], v[210:213], v[182:185], v[20:23]
	v_mfma_f32_16x16x32_bf16 v[16:19], v[218:221], v[182:185], v[16:19]
	v_mfma_f32_16x16x32_bf16 v[4:7], v[210:213], v[202:205], v[4:7]
	v_mfma_f32_16x16x32_bf16 v[0:3], v[218:221], v[202:205], v[0:3]
	s_add_i32 s20, 0, 0x18000
	v_add_u32_e32 v149, s20, v144
	s_barrier
	ds_read_b128 v[138:141], v149
	ds_read_b128 v[150:153], v149 offset:1024
	ds_read_b128 v[154:157], v149 offset:2048
	ds_read_b128 v[158:161], v149 offset:3072
	s_add_u32 s18, s18, s2
	s_addc_u32 s19, s19, s3
	s_mov_b32 m0, s27
	ds_read_b128 v[162:165], v148 offset:32768
	ds_read_b128 v[166:169], v148 offset:33792
	ds_read_b128 v[170:173], v148 offset:34816
	ds_read_b128 v[174:177], v148 offset:35840
	ds_read_b128 v[178:181], v148 offset:36864
	ds_read_b128 v[182:185], v148 offset:37888
	ds_read_b128 v[186:189], v148 offset:38912
	ds_read_b128 v[202:205], v148 offset:39936
	global_load_lds_dwordx4 v128, s[18:19]
	s_mov_b32 m0, s28
	s_nop 0
	global_load_lds_dwordx4 v130, s[18:19]
	s_waitcnt lgkmcnt(8)
	s_barrier
	s_waitcnt lgkmcnt(0)
	s_waitcnt lgkmcnt(0)
	v_mfma_f32_16x16x32_bf16 v[124:127], v[138:141], v[162:165], v[124:127]
	v_mfma_f32_16x16x32_bf16 v[120:123], v[154:157], v[162:165], v[120:123]
	v_mfma_f32_16x16x32_bf16 v[108:111], v[138:141], v[170:173], v[108:111]
	v_mfma_f32_16x16x32_bf16 v[104:107], v[154:157], v[170:173], v[104:107]
	v_mfma_f32_16x16x32_bf16 v[92:95], v[138:141], v[178:181], v[92:95]
	v_mfma_f32_16x16x32_bf16 v[88:91], v[154:157], v[178:181], v[88:91]
	v_mfma_f32_16x16x32_bf16 v[76:79], v[138:141], v[186:189], v[76:79]
	v_mfma_f32_16x16x32_bf16 v[72:75], v[154:157], v[186:189], v[72:75]
	v_mfma_f32_16x16x32_bf16 v[124:127], v[150:153], v[166:169], v[124:127]
	v_mfma_f32_16x16x32_bf16 v[120:123], v[158:161], v[166:169], v[120:123]
	v_mfma_f32_16x16x32_bf16 v[108:111], v[150:153], v[174:177], v[108:111]
	v_mfma_f32_16x16x32_bf16 v[104:107], v[158:161], v[174:177], v[104:107]
	v_mfma_f32_16x16x32_bf16 v[92:95], v[150:153], v[182:185], v[92:95]
	v_mfma_f32_16x16x32_bf16 v[88:91], v[158:161], v[182:185], v[88:91]
	v_mfma_f32_16x16x32_bf16 v[76:79], v[150:153], v[202:205], v[76:79]
	v_mfma_f32_16x16x32_bf16 v[72:75], v[158:161], v[202:205], v[72:75]
	s_barrier
	s_add_i32 s18, 0, 0x1c000
	s_add_i32 s19, s20, s24
	v_add_u32_e32 v149, s18, v144
	s_mov_b32 m0, s19
	ds_read_b128 v[206:209], v149
	ds_read_b128 v[210:213], v149 offset:1024
	ds_read_b128 v[214:217], v149 offset:2048
	ds_read_b128 v[218:221], v149 offset:3072
	global_load_lds_dwordx4 v194, s[80:81]
	s_add_i32 m0, s19, 0x2000
	s_nop 0
	global_load_lds_dwordx4 v132, s[80:81]
	s_barrier
; #define PG8_STAGE(bufoff, gbase, voff) do { _Pragma("unroll") for (int _i = 0; _i < 2; ++_i) \
;         __builtin_amdgcn_global_load_lds((const unsigned*)((const char*)(gbase) + (voff)[_i]), (LAS unsigned*)(lds + (bufoff) + ldsw + _i * 8192), 16, 0, 0); } while (0)
; #define PG8_LDA(dst, b, h) do { _Pragma("unroll") for (int m = 0; m < 4; ++m) _Pragma("unroll") for (int k = 0; k < 2; ++k) dst[m][k] = *(const LAS bf16x8*)(lds + PG8_SA(b, h) + aoff + m * 2048 + k * 1024); } while (0)
; #define PG8_LDB(dst, b, h) do { _Pragma("unroll") for (int n = 0; n < 2; ++n) _Pragma("unroll") for (int k = 0; k < 2; ++k) dst[n][k] = *(const LAS bf16x8*)(lds + PG8_SB(b, h) + boff + n * 2048 + k * 1024); } while (0)
; #define PG8_MMA(ai, bj, At, Bt) do { __builtin_amdgcn_s_setprio(1); _Pragma("unroll") for (int m = 0; m < 4; ++m) _Pragma("unroll") for (int n = 0; n < 2; ++n) _Pragma("unroll") for (int k = 0; k < 2; ++k) \
;         acc[ai][bj][m][n] = __builtin_amdgcn_mfma_f32_16x16x32_bf16(Bt[n][k], At[m][k], acc[ai][bj][m][n], 0, 0, 0); __builtin_amdgcn_s_setprio(0); } while (0)
; #define PG8_WAIT_V(n) asm volatile("s_waitcnt vmcnt(" #n ")" ::: "memory")
; #define PG8_WAIT_L(n) asm volatile("s_waitcnt lgkmcnt(" #n ")" ::: "memory")
; #define PG8_BAR __builtin_amdgcn_s_barrier()
; #define PG8_SCHED __builtin_amdgcn_sched_barrier(0)
; template <class Epi>
; __device__ __forceinline__ void gemm_phase(LAS unsigned char* lds, const Gemm g, const StaticOrder& S, const Epi& E) {
;     ...
;             PG8_LDB(B1, 1, 1); PG8_STAGE(PG8_SB(1, 0), b3, voffB);
;             PG8_BAR; PG8_WAIT_L(0); PG8_MMA(0, 1, At, B1); PG8_BAR;
;             PG8_LDA(At, 1, 1); PG8_STAGE(PG8_SA(1, 0), a3, voffA);
;             PG8_BAR; PG8_WAIT_L(0); PG8_MMA(1, 0, At, B0); PG8_BAR; PG8_SCHED;
;             PG8_STAGE(PG8_SB(1, 1), b3 + hstep, voffB);
;             PG8_WAIT_V(6); PG8_BAR; PG8_MMA(1, 1, At, B1); PG8_BAR;
	s_waitcnt lgkmcnt(0)
	s_waitcnt lgkmcnt(0)
	v_mfma_f32_16x16x32_bf16 v[116:119], v[206:209], v[162:165], v[116:119]
	v_mfma_f32_16x16x32_bf16 v[112:115], v[214:217], v[162:165], v[112:115]
	v_mfma_f32_16x16x32_bf16 v[100:103], v[206:209], v[170:173], v[100:103]
	v_mfma_f32_16x16x32_bf16 v[96:99], v[214:217], v[170:173], v[96:99]
	v_mfma_f32_16x16x32_bf16 v[84:87], v[206:209], v[178:181], v[84:87]
	v_mfma_f32_16x16x32_bf16 v[80:83], v[214:217], v[178:181], v[80:83]
	v_mfma_f32_16x16x32_bf16 v[68:71], v[206:209], v[186:189], v[68:71]
	v_mfma_f32_16x16x32_bf16 v[64:67], v[214:217], v[186:189], v[64:67]
	v_mfma_f32_16x16x32_bf16 v[116:119], v[210:213], v[166:169], v[116:119]
	v_mfma_f32_16x16x32_bf16 v[112:115], v[218:221], v[166:169], v[112:115]
	v_mfma_f32_16x16x32_bf16 v[100:103], v[210:213], v[174:177], v[100:103]
	v_mfma_f32_16x16x32_bf16 v[96:99], v[218:221], v[174:177], v[96:99]
	v_mfma_f32_16x16x32_bf16 v[84:87], v[210:213], v[182:185], v[84:87]
	v_mfma_f32_16x16x32_bf16 v[80:83], v[218:221], v[182:185], v[80:83]
	v_mfma_f32_16x16x32_bf16 v[68:71], v[210:213], v[202:205], v[68:71]
	v_mfma_f32_16x16x32_bf16 v[64:67], v[218:221], v[202:205], v[64:67]
	s_mov_b32 m0, s29
	s_barrier
	ds_read_b128 v[162:165], v148 offset:49152
	ds_read_b128 v[166:169], v148 offset:50176
	ds_read_b128 v[170:173], v148 offset:51200
	ds_read_b128 v[174:177], v148 offset:52224
	ds_read_b128 v[178:181], v148 offset:53248
	ds_read_b128 v[182:185], v148 offset:54272
	ds_read_b128 v[186:189], v148 offset:55296
	ds_read_b128 v[202:205], v148 offset:56320
	global_load_lds_dwordx4 v128, s[82:83]
	s_mov_b32 m0, s30
	s_nop 0
	global_load_lds_dwordx4 v130, s[82:83]
	s_barrier
	s_waitcnt lgkmcnt(0)
	s_waitcnt lgkmcnt(0)
	v_mfma_f32_16x16x32_bf16 v[60:63], v[138:141], v[162:165], v[60:63]
	v_mfma_f32_16x16x32_bf16 v[56:59], v[154:157], v[162:165], v[56:59]
	v_mfma_f32_16x16x32_bf16 v[44:47], v[138:141], v[170:173], v[44:47]
	v_mfma_f32_16x16x32_bf16 v[40:43], v[154:157], v[170:173], v[40:43]
	v_mfma_f32_16x16x32_bf16 v[28:31], v[138:141], v[178:181], v[28:31]
	v_mfma_f32_16x16x32_bf16 v[24:27], v[154:157], v[178:181], v[24:27]
	v_mfma_f32_16x16x32_bf16 v[12:15], v[138:141], v[186:189], v[12:15]
	v_mfma_f32_16x16x32_bf16 v[8:11], v[154:157], v[186:189], v[8:11]
	v_mfma_f32_16x16x32_bf16 v[60:63], v[150:153], v[166:169], v[60:63]
	v_mfma_f32_16x16x32_bf16 v[56:59], v[158:161], v[166:169], v[56:59]
	v_mfma_f32_16x16x32_bf16 v[44:47], v[150:153], v[174:177], v[44:47]
	v_mfma_f32_16x16x32_bf16 v[40:43], v[158:161], v[174:177], v[40:43]
	v_mfma_f32_16x16x32_bf16 v[28:31], v[150:153], v[182:185], v[28:31]
	v_mfma_f32_16x16x32_bf16 v[24:27], v[158:161], v[182:185], v[24:27]
	v_mfma_f32_16x16x32_bf16 v[12:15], v[150:153], v[202:205], v[12:15]
	v_mfma_f32_16x16x32_bf16 v[8:11], v[158:161], v[202:205], v[8:11]
	s_barrier
	s_add_i32 s18, s18, s24
	s_mov_b32 m0, s18
	s_nop 0
	global_load_lds_dwordx4 v194, s[84:85]
	s_add_i32 m0, s18, 0x2000
	s_nop 0
	global_load_lds_dwordx4 v132, s[84:85]
	s_waitcnt vmcnt(6)
	s_barrier
	v_mfma_f32_16x16x32_bf16 v[52:55], v[206:209], v[162:165], v[52:55]
	v_mfma_f32_16x16x32_bf16 v[48:51], v[214:217], v[162:165], v[48:51]
	v_mfma_f32_16x16x32_bf16 v[36:39], v[206:209], v[170:173], v[36:39]
	v_mfma_f32_16x16x32_bf16 v[32:35], v[214:217], v[170:173], v[32:35]
	v_mfma_f32_16x16x32_bf16 v[20:23], v[206:209], v[178:181], v[20:23]
	v_mfma_f32_16x16x32_bf16 v[16:19], v[214:217], v[178:181], v[16:19]
	v_mfma_f32_16x16x32_bf16 v[4:7], v[206:209], v[186:189], v[4:7]
	v_mfma_f32_16x16x32_bf16 v[0:3], v[214:217], v[186:189], v[0:3]
	v_mfma_f32_16x16x32_bf16 v[52:55], v[210:213], v[166:169], v[52:55]
	v_mfma_f32_16x16x32_bf16 v[48:51], v[218:221], v[166:169], v[48:51]
	v_mfma_f32_16x16x32_bf16 v[36:39], v[210:213], v[174:177], v[36:39]
	v_mfma_f32_16x16x32_bf16 v[32:35], v[218:221], v[174:177], v[32:35]
	v_mfma_f32_16x16x32_bf16 v[20:23], v[210:213], v[182:185], v[20:23]
	v_mfma_f32_16x16x32_bf16 v[16:19], v[218:221], v[182:185], v[16:19]
	v_mfma_f32_16x16x32_bf16 v[4:7], v[210:213], v[202:205], v[4:7]
	v_mfma_f32_16x16x32_bf16 v[0:3], v[218:221], v[202:205], v[0:3]
	s_add_u32 s40, s40, 0x100
	s_addc_u32 s41, s41, 0
	s_add_u32 s16, s16, 0x100
	s_addc_u32 s17, s17, 0
	s_cmp_ge_i32 s42, s31
	s_mov_b32 s18, s42
	s_barrier
	s_cbranch_scc0 .LBB0_528
